# P3 loop: K-address adds and DMA pointer advances moved from the post-barrier head to the previous iteration's tail (VALU-free segment head)
# speedup vs baseline: 1.0158x; 1.0066x over previous
.Lk_top:
	ds_read_b128 v[80:83], v85 offset:16384
	ds_read_b128 v[202:205], v254 offset:16384
	ds_read_b128 v[194:197], v255 offset:16384
	ds_read_b128 v[186:189], v84 offset:16384
	ds_read_b128 v[198:201], v85 offset:20480
	ds_read_b128 v[190:193], v254 offset:20480
	ds_read_b128 v[246:249], v255 offset:20480
	ds_read_b128 v[250:253], v84 offset:20480
	s_cmp_ge_i32 s72, s98
	s_cbranch_scc1 .LBB0_325
	s_add_i32 m0, s1, s94
	s_add_i32 s4, s90, s1
	global_load_lds_dwordx4 v[220:221], off
	s_mov_b32 m0, s4
	s_add_i32 s4, s1, s66
	global_load_lds_dwordx4 v[218:219], off
	s_mov_b32 m0, s4
	global_load_lds_dwordx4 v[224:225], off
	global_load_lds_dwordx4 v[224:225], off offset:1024

.LBB0_327:
	s_waitcnt lgkmcnt(4)
	v_mfma_f32_32x32x16_bf16 v[48:63], v[182:185], v[174:177], v[48:63]
	v_add_f32_e32 v190, v255, v80
	v_exp_f32_e32 v190, v190
	ds_read_b64_tr_b16 v[246:247], v158 offset:36864
	ds_read_b64_tr_b16 v[248:249], v158 offset:38912
	v_add_f32_e32 v157, v190, v96
	v_mfma_f32_32x32x16_bf16 v[32:47], v[178:181], v[174:177], v[32:47]
	v_add_f32_e32 v191, v255, v81
	v_exp_f32_e32 v191, v191
	ds_read_b64_tr_b16 v[250:251], v159 offset:36864
	ds_read_b64_tr_b16 v[252:253], v159 offset:38912
	v_add_f32_e32 v156, v191, v97
	v_add_f32_e32 v157, v156, v157
	s_waitcnt lgkmcnt(4)
	v_mfma_f32_32x32x16_bf16 v[16:31], v[148:151], v[174:177], v[16:31]
	v_add_f32_e32 v192, v255, v82
	v_exp_f32_e32 v192, v192
	ds_read_b64_tr_b16 v[182:183], v160 offset:36864
	ds_read_b64_tr_b16 v[184:185], v160 offset:38912
	v_add_f32_e32 v156, v192, v98
	v_add_f32_e32 v157, v156, v157
	v_mfma_f32_32x32x16_bf16 v[0:15], v[152:155], v[174:177], v[0:15]
	v_add_f32_e32 v193, v255, v83
	v_exp_f32_e32 v193, v193
	ds_read_b64_tr_b16 v[178:179], v161 offset:36864
	ds_read_b64_tr_b16 v[180:181], v161 offset:38912
	v_add_f32_e32 v156, v193, v99
	v_add_f32_e32 v157, v156, v157
	v_cvt_pk_bf16_f32 v174, v96, v97
	s_waitcnt lgkmcnt(4)
	v_mfma_f32_32x32x16_bf16 v[48:63], v[246:249], v[162:165], v[48:63]
	v_add_f32_e32 v194, v255, v84
	v_exp_f32_e32 v194, v194
	ds_read_b64_tr_b16 v[148:149], v158 offset:40960
	ds_read_b64_tr_b16 v[150:151], v158 offset:43008
	v_add_f32_e32 v156, v194, v100
	v_add_f32_e32 v157, v156, v157
	v_cvt_pk_bf16_f32 v175, v98, v99
	v_mfma_f32_32x32x16_bf16 v[32:47], v[250:253], v[162:165], v[32:47]
	v_add_f32_e32 v195, v255, v85
	v_exp_f32_e32 v195, v195
	ds_read_b64_tr_b16 v[152:153], v159 offset:40960
	ds_read_b64_tr_b16 v[154:155], v159 offset:43008
	v_add_f32_e32 v156, v195, v101
	v_add_f32_e32 v157, v156, v157
	v_cvt_pk_bf16_f32 v176, v100, v101
	s_waitcnt lgkmcnt(4)
	v_mfma_f32_32x32x16_bf16 v[16:31], v[182:185], v[162:165], v[16:31]
	v_add_f32_e32 v196, v255, v86
	v_exp_f32_e32 v196, v196
	ds_read_b64_tr_b16 v[246:247], v160 offset:40960
	ds_read_b64_tr_b16 v[248:249], v160 offset:43008
	v_add_f32_e32 v156, v196, v102
	v_add_f32_e32 v157, v156, v157
	v_cvt_pk_bf16_f32 v177, v102, v103
	v_mfma_f32_32x32x16_bf16 v[0:15], v[178:181], v[162:165], v[0:15]
	v_add_f32_e32 v197, v255, v87
	v_exp_f32_e32 v197, v197
	ds_read_b64_tr_b16 v[250:251], v161 offset:40960
	ds_read_b64_tr_b16 v[252:253], v161 offset:43008
	v_add_f32_e32 v156, v197, v103
	v_add_f32_e32 v157, v156, v157
	v_cvt_pk_bf16_f32 v162, v104, v105
	s_waitcnt lgkmcnt(4)
	v_mfma_f32_32x32x16_bf16 v[48:63], v[148:151], v[170:173], v[48:63]
	v_add_f32_e32 v198, v255, v88
	v_exp_f32_e32 v198, v198
	ds_read_b64_tr_b16 v[182:183], v158 offset:45056
	ds_read_b64_tr_b16 v[184:185], v158 offset:47104
	v_add_f32_e32 v156, v198, v104
	v_add_f32_e32 v157, v156, v157
	v_cvt_pk_bf16_f32 v163, v106, v107
	v_mfma_f32_32x32x16_bf16 v[32:47], v[152:155], v[170:173], v[32:47]
	v_add_f32_e32 v199, v255, v89
	v_exp_f32_e32 v199, v199
	ds_read_b64_tr_b16 v[178:179], v159 offset:45056
	ds_read_b64_tr_b16 v[180:181], v159 offset:47104
	v_add_f32_e32 v156, v199, v105
	v_add_f32_e32 v157, v156, v157
	v_cvt_pk_bf16_f32 v164, v108, v109
	s_waitcnt lgkmcnt(4)
	v_mfma_f32_32x32x16_bf16 v[16:31], v[246:249], v[170:173], v[16:31]
	v_add_f32_e32 v200, v255, v90
	v_exp_f32_e32 v200, v200
	ds_read_b64_tr_b16 v[148:149], v160 offset:45056
	ds_read_b64_tr_b16 v[150:151], v160 offset:47104
	v_add_f32_e32 v156, v200, v106
	v_add_f32_e32 v157, v156, v157
	v_cvt_pk_bf16_f32 v165, v110, v111
	v_mfma_f32_32x32x16_bf16 v[0:15], v[250:253], v[170:173], v[0:15]
	v_add_f32_e32 v201, v255, v91
	v_exp_f32_e32 v201, v201
	ds_read_b64_tr_b16 v[152:153], v161 offset:45056
	ds_read_b64_tr_b16 v[154:155], v161 offset:47104
	v_add_f32_e32 v156, v201, v107
	v_add_f32_e32 v157, v156, v157
	v_cvt_pk_bf16_f32 v170, v190, v191
	s_waitcnt lgkmcnt(4)
	v_mfma_f32_32x32x16_bf16 v[48:63], v[182:185], v[166:169], v[48:63]
	v_add_f32_e32 v202, v255, v92
	v_exp_f32_e32 v202, v202
	v_cvt_pk_bf16_f32 v171, v192, v193
	v_add_f32_e32 v156, v202, v108
	v_add_f32_e32 v157, v156, v157
	v_mfma_f32_32x32x16_bf16 v[32:47], v[178:181], v[166:169], v[32:47]
	v_add_f32_e32 v203, v255, v93
	v_exp_f32_e32 v203, v203
	v_cvt_pk_bf16_f32 v172, v194, v195
	v_add_f32_e32 v156, v203, v109
	v_add_f32_e32 v157, v156, v157
	s_waitcnt lgkmcnt(0)
	v_mfma_f32_32x32x16_bf16 v[16:31], v[148:151], v[166:169], v[16:31]
	v_add_f32_e32 v204, v255, v94
	v_exp_f32_e32 v204, v204
	v_cvt_pk_bf16_f32 v173, v196, v197
	v_add_f32_e32 v156, v204, v110
	v_add_f32_e32 v157, v156, v157
	v_mfma_f32_32x32x16_bf16 v[0:15], v[152:155], v[166:169], v[0:15]
	v_add_f32_e32 v205, v255, v95
	v_exp_f32_e32 v205, v205
	v_cvt_pk_bf16_f32 v166, v198, v199
	v_add_f32_e32 v156, v205, v111
	v_add_f32_e32 v157, v156, v157
	v_cvt_pk_bf16_f32 v167, v200, v201
	v_cvt_pk_bf16_f32 v168, v202, v203
	v_cvt_pk_bf16_f32 v169, v204, v205
	s_add_i32 s72, s72, 1
	s_add_i32 s79, s79, 0x8000
	s_add_i32 s100, s100, 64
	v_add_f32_e32 v229, v229, v157
	v_lshl_add_u64 v[218:219], v[218:219], 0, s[88:89]
	v_lshl_add_u64 v[220:221], v[220:221], 0, s[88:89]
	v_lshl_add_u64 v[224:225], v[224:225], 0, s[92:93]
	s_and_b32 s1, s79, 0x18000
	s_xor_b32 s0, s1, 0x10000
	v_add_u32_e32 v85, s0, v222
	v_add_u32_e32 v254, s0, v223
	v_add_u32_e32 v255, s0, v241
	v_add_u32_e32 v84, s0, v242
	s_cmp_ge_i32 s72, s99
	s_cbranch_scc1 .LBB0_332
	s_cmp_ge_i32 s72, s73
	s_cbranch_scc1 .Lk_last
	s_waitcnt vmcnt(4) lgkmcnt(0)
	s_barrier
	s_branch .Lk_top
